# sgemm MODE0 tile loads + sample-attn QK loads pipelined (all loads issued, counted vmcnt)
# baseline (speedup 1.0000x reference)
; __device__ __forceinline__ unsigned cvt_pk_bf16(float lo, float hi) { unsigned r; asm volatile("v_cvt_pk_bf16_f32 %0, %1, %2" : "=v"(r) : "v"(lo), "v"(hi)); return r; }
; __device__ __forceinline__ void sample_attn(Frame& F, int l, int item) {
;     ...
;     const int r16 = lane & 15, quad = lane >> 4;
;     const bf16_t* qp = Q + (size_t)(MP + b * 16 + r16) * D + h * 256 + quad * 8;
; #pragma unroll
;     for (int kk = 0; kk < 2; ++kk) {
;         const int kt = 2 * w + kk; const float* kp = CK + (size_t)(kt * 16 + r16) * 1024 + quad * 8;
;         f32x4 acc = (f32x4){0.f, 0.f, 0.f, 0.f};
; #pragma unroll
;         for (int c = 0; c < 8; ++c) { const bf16x8 a = *(const bf16x8*)(qp + 32 * c); const f32x4 k0 = *(const f32x4*)(kp + 32 * c), k1 = *(const f32x4*)(kp + 32 * c + 4);
;             u32x4 kb; kb.x = cvt_pk_bf16(k0.x, k0.y); kb.y = cvt_pk_bf16(k0.z, k0.w); kb.z = cvt_pk_bf16(k1.x, k1.y); kb.w = cvt_pk_bf16(k1.z, k1.w);
;             acc = __builtin_amdgcn_mfma_f32_16x16x32_bf16(a, __builtin_bit_cast(bf16x8, kb), acc, 0, 0, 0); }
; #pragma unroll
;         for (int j = 0; j < 4; ++j) Ssm[(quad * 4 + j) * SP + kt * 16 + r16] = acc[j];
;     }
.LBB0_578:
	s_ashr_i32 s2, s8, 4
	s_add_i32 s2, s2, s6
	s_lshl_b32 s18, s7, 2
	s_ashr_i32 s3, s2, 31
	v_readlane_b32 s52, v254, 18
	s_and_b32 s19, s18, 0xc00
	s_lshl_b64 s[4:5], s[2:3], 20
	v_readlane_b32 s58, v254, 24
	v_readlane_b32 s59, v254, 25
	s_add_u32 s2, s58, s4
	s_addc_u32 s3, s59, s5
	s_lshl_b32 s10, s8, 6
	s_and_b32 s9, s10, 0x300
	s_lshl_b32 s11, s9, 2
	s_add_u32 s2, s2, s11
	v_mov_b32_e32 v0, v163
	s_addc_u32 s3, s3, 0
	s_and_b32 s11, s8, -16
	s_add_i32 s11, s11, 0x8000
	v_and_b32_e32 v6, 15, v0
	v_or_b32_e32 v2, s11, v6
	v_ashrrev_i32_e32 v3, 31, v2
	v_lshlrev_b64 v[2:3], 11, v[2:3]
	v_lshl_add_u64 v[2:3], s[16:17], 0, v[2:3]
	s_lshl_b32 s46, s9, 1
	v_and_b32_e32 v11, 63, v0
	v_ashrrev_i32_e32 v13, 6, v0
	v_bfe_u32 v10, v0, 4, 2
	v_lshl_add_u64 v[2:3], v[2:3], 0, s[46:47]
	v_and_b32_e32 v0, 48, v0
	v_readfirstlane_b32 s20, v13
	v_lshl_add_u64 v[2:3], v[2:3], 0, v[0:1]
	v_lshlrev_b32_e32 v0, 5, v10
	v_lshl_add_u64 v[4:5], s[2:3], 0, v[0:1]
	v_lshlrev_b32_e32 v0, 2, v6
	v_lshl_or_b32 v6, s20, 5, v6
	v_ashrrev_i32_e32 v7, 31, v6
	v_lshlrev_b64 v[8:9], 12, v[6:7]
	v_lshl_add_u64 v[8:9], v[4:5], 0, v[8:9]
	s_lshl_b32 s2, s20, 7
	s_add_i32 s2, s2, 0
	v_mul_u32_u24_e32 v7, 0x1040, v10
	v_or_b32_e32 v6, 16, v6
	v_add3_u32 v0, s2, v0, v7
	v_ashrrev_i32_e32 v7, 31, v6
	v_lshlrev_b64 v[6:7], 12, v[6:7]
	v_lshl_add_u64 v[4:5], v[4:5], 0, v[6:7]
	s_mul_i32 s2, s20, 0x820
	s_add_i32 s2, s2, 0
	v_readlane_b32 s60, v254, 26
	v_readlane_b32 s61, v254, 27
	v_readlane_b32 s53, v254, 19
	v_readlane_b32 s54, v254, 20
	v_readlane_b32 s55, v254, 21
	v_readlane_b32 s56, v254, 22
	v_readlane_b32 s57, v254, 23
	v_readlane_b32 s62, v254, 28
	v_readlane_b32 s63, v254, 29
	v_readlane_b32 s64, v254, 30
	v_readlane_b32 s65, v254, 31
	v_readlane_b32 s66, v254, 32
	v_readlane_b32 s67, v254, 33
	global_load_dwordx4 v[34:37], v[2:3], off
	global_load_dwordx4 v[66:69], v[8:9], off offset:16
	global_load_dwordx4 v[70:73], v[8:9], off
	global_load_dwordx4 v[38:41], v[2:3], off offset:64
	global_load_dwordx4 v[74:77], v[8:9], off offset:144
	global_load_dwordx4 v[78:81], v[8:9], off offset:128
	global_load_dwordx4 v[42:45], v[2:3], off offset:128
	global_load_dwordx4 v[82:85], v[8:9], off offset:272
	global_load_dwordx4 v[86:89], v[8:9], off offset:256
	global_load_dwordx4 v[46:49], v[2:3], off offset:192
	global_load_dwordx4 v[90:93], v[8:9], off offset:400
	global_load_dwordx4 v[94:97], v[8:9], off offset:384
	global_load_dwordx4 v[50:53], v[2:3], off offset:256
	global_load_dwordx4 v[190:193], v[8:9], off offset:528
	global_load_dwordx4 v[194:197], v[8:9], off offset:512
	global_load_dwordx4 v[54:57], v[2:3], off offset:320
	global_load_dwordx4 v[198:201], v[8:9], off offset:656
	global_load_dwordx4 v[202:205], v[8:9], off offset:640
	global_load_dwordx4 v[58:61], v[2:3], off offset:384
	global_load_dwordx4 v[206:209], v[8:9], off offset:784
	global_load_dwordx4 v[210:213], v[8:9], off offset:768
	global_load_dwordx4 v[62:65], v[2:3], off offset:448
	global_load_dwordx4 v[214:217], v[8:9], off offset:912
	global_load_dwordx4 v[218:221], v[8:9], off offset:896
	global_load_dwordx4 v[222:225], v[4:5], off offset:16
	global_load_dwordx4 v[226:229], v[4:5], off
	global_load_dwordx4 v[230:233], v[4:5], off offset:144
	global_load_dwordx4 v[234:237], v[4:5], off offset:128
	global_load_dwordx4 v[238:241], v[4:5], off offset:272
	global_load_dwordx4 v[242:245], v[4:5], off offset:256
	global_load_dwordx4 v[246:249], v[4:5], off offset:400
	global_load_dwordx4 v[250:253], v[4:5], off offset:384
	global_load_dwordx4 v[132:135], v[4:5], off offset:528
	global_load_dwordx4 v[136:139], v[4:5], off offset:512
	global_load_dwordx4 v[140:143], v[4:5], off offset:656
	global_load_dwordx4 v[144:147], v[4:5], off offset:640
	global_load_dwordx4 v[148:151], v[4:5], off offset:784
	global_load_dwordx4 v[152:155], v[4:5], off offset:768
	global_load_dwordx4 v[156:159], v[4:5], off offset:912
	global_load_dwordx4 v[164:167], v[4:5], off offset:896
	s_waitcnt vmcnt(37)
	v_cvt_pk_bf16_f32 v70, v70, v71
	v_cvt_pk_bf16_f32 v71, v72, v73
	v_cvt_pk_bf16_f32 v72, v66, v67
	v_cvt_pk_bf16_f32 v73, v68, v69
	s_waitcnt vmcnt(34)
	v_cvt_pk_bf16_f32 v78, v78, v79
	v_cvt_pk_bf16_f32 v79, v80, v81
	v_cvt_pk_bf16_f32 v80, v74, v75
	v_cvt_pk_bf16_f32 v81, v76, v77
	v_mfma_f32_16x16x32_bf16 v[14:17], v[34:37], v[70:73], 0
	s_waitcnt vmcnt(31)
	v_cvt_pk_bf16_f32 v86, v86, v87
	v_cvt_pk_bf16_f32 v87, v88, v89
	v_cvt_pk_bf16_f32 v88, v82, v83
	v_cvt_pk_bf16_f32 v89, v84, v85
	v_mfma_f32_16x16x32_bf16 v[14:17], v[38:41], v[78:81], v[14:17]
	s_waitcnt vmcnt(28)
	v_cvt_pk_bf16_f32 v94, v94, v95
	v_cvt_pk_bf16_f32 v95, v96, v97
	v_cvt_pk_bf16_f32 v96, v90, v91
	v_cvt_pk_bf16_f32 v97, v92, v93
	v_mfma_f32_16x16x32_bf16 v[14:17], v[42:45], v[86:89], v[14:17]
	s_waitcnt vmcnt(25)
	v_cvt_pk_bf16_f32 v194, v194, v195
	v_cvt_pk_bf16_f32 v195, v196, v197
	v_cvt_pk_bf16_f32 v196, v190, v191
	v_cvt_pk_bf16_f32 v197, v192, v193
	v_mfma_f32_16x16x32_bf16 v[14:17], v[46:49], v[94:97], v[14:17]
	s_waitcnt vmcnt(22)
	v_cvt_pk_bf16_f32 v202, v202, v203
	v_cvt_pk_bf16_f32 v203, v204, v205
	v_cvt_pk_bf16_f32 v204, v198, v199
	v_cvt_pk_bf16_f32 v205, v200, v201
	v_mfma_f32_16x16x32_bf16 v[14:17], v[50:53], v[194:197], v[14:17]
	s_waitcnt vmcnt(19)
	v_cvt_pk_bf16_f32 v210, v210, v211
	v_cvt_pk_bf16_f32 v211, v212, v213
	v_cvt_pk_bf16_f32 v212, v206, v207
	v_cvt_pk_bf16_f32 v213, v208, v209
	v_mfma_f32_16x16x32_bf16 v[14:17], v[54:57], v[202:205], v[14:17]
	s_waitcnt vmcnt(16)
; __device__ __forceinline__ unsigned cvt_pk_bf16(float lo, float hi) { unsigned r; asm volatile("v_cvt_pk_bf16_f32 %0, %1, %2" : "=v"(r) : "v"(lo), "v"(hi)); return r; }
; __device__ __forceinline__ void sample_attn(Frame& F, int l, int item) {
;     ...
;     for (int kk = 0; kk < 2; ++kk) {
;         const int kt = 2 * w + kk; const float* kp = CK + (size_t)(kt * 16 + r16) * 1024 + quad * 8;
;         f32x4 acc = (f32x4){0.f, 0.f, 0.f, 0.f};
; #pragma unroll
;         for (int c = 0; c < 8; ++c) { const bf16x8 a = *(const bf16x8*)(qp + 32 * c); const f32x4 k0 = *(const f32x4*)(kp + 32 * c), k1 = *(const f32x4*)(kp + 32 * c + 4);
;             u32x4 kb; kb.x = cvt_pk_bf16(k0.x, k0.y); kb.y = cvt_pk_bf16(k0.z, k0.w); kb.z = cvt_pk_bf16(k1.x, k1.y); kb.w = cvt_pk_bf16(k1.z, k1.w);
;             acc = __builtin_amdgcn_mfma_f32_16x16x32_bf16(a, __builtin_bit_cast(bf16x8, kb), acc, 0, 0, 0); }
; #pragma unroll
;         for (int j = 0; j < 4; ++j) Ssm[(quad * 4 + j) * SP + kt * 16 + r16] = acc[j];
;     }
;     __syncthreads();
	v_cvt_pk_bf16_f32 v218, v218, v219
	v_cvt_pk_bf16_f32 v219, v220, v221
	v_cvt_pk_bf16_f32 v220, v214, v215
	v_cvt_pk_bf16_f32 v221, v216, v217
	v_mfma_f32_16x16x32_bf16 v[14:17], v[58:61], v[210:213], v[14:17]
	s_nop 1
	v_mfma_f32_16x16x32_bf16 v[14:17], v[62:65], v[218:221], v[14:17]
	s_waitcnt vmcnt(14)
	v_cvt_pk_bf16_f32 v226, v226, v227
	v_cvt_pk_bf16_f32 v227, v228, v229
	v_cvt_pk_bf16_f32 v228, v222, v223
	v_cvt_pk_bf16_f32 v229, v224, v225
	s_waitcnt vmcnt(12)
	v_cvt_pk_bf16_f32 v234, v234, v235
	v_cvt_pk_bf16_f32 v235, v236, v237
	v_cvt_pk_bf16_f32 v236, v230, v231
	v_cvt_pk_bf16_f32 v237, v232, v233
	v_mfma_f32_16x16x32_bf16 v[2:5], v[34:37], v[226:229], 0
	s_waitcnt vmcnt(10)
	v_cvt_pk_bf16_f32 v242, v242, v243
	v_cvt_pk_bf16_f32 v243, v244, v245
	v_cvt_pk_bf16_f32 v244, v238, v239
	v_cvt_pk_bf16_f32 v245, v240, v241
	v_mfma_f32_16x16x32_bf16 v[2:5], v[38:41], v[234:237], v[2:5]
	s_waitcnt vmcnt(8)
	v_cvt_pk_bf16_f32 v250, v250, v251
	v_cvt_pk_bf16_f32 v251, v252, v253
	v_cvt_pk_bf16_f32 v252, v246, v247
	v_cvt_pk_bf16_f32 v253, v248, v249
	v_mfma_f32_16x16x32_bf16 v[2:5], v[42:45], v[242:245], v[2:5]
	s_waitcnt vmcnt(6)
	v_cvt_pk_bf16_f32 v136, v136, v137
	v_cvt_pk_bf16_f32 v137, v138, v139
	v_cvt_pk_bf16_f32 v138, v132, v133
	v_cvt_pk_bf16_f32 v139, v134, v135
	v_mfma_f32_16x16x32_bf16 v[2:5], v[46:49], v[250:253], v[2:5]
	s_waitcnt vmcnt(4)
	v_cvt_pk_bf16_f32 v144, v144, v145
	v_cvt_pk_bf16_f32 v145, v146, v147
	v_cvt_pk_bf16_f32 v146, v140, v141
	v_cvt_pk_bf16_f32 v147, v142, v143
	v_mfma_f32_16x16x32_bf16 v[2:5], v[50:53], v[136:139], v[2:5]
	s_waitcnt vmcnt(2)
	v_cvt_pk_bf16_f32 v152, v152, v153
	v_cvt_pk_bf16_f32 v153, v154, v155
	v_cvt_pk_bf16_f32 v154, v148, v149
	v_cvt_pk_bf16_f32 v155, v150, v151
	v_mfma_f32_16x16x32_bf16 v[2:5], v[54:57], v[144:147], v[2:5]
	s_waitcnt vmcnt(0)
	v_cvt_pk_bf16_f32 v164, v164, v165
	v_cvt_pk_bf16_f32 v165, v166, v167
	v_cvt_pk_bf16_f32 v166, v156, v157
	v_cvt_pk_bf16_f32 v167, v158, v159
	v_mfma_f32_16x16x32_bf16 v[2:5], v[58:61], v[152:155], v[2:5]
	s_nop 1
	v_mfma_f32_16x16x32_bf16 v[2:5], v[62:65], v[164:167], v[2:5]
	s_nop 7
	ds_write_b32 v0, v14
	ds_write_b32 v0, v15 offset:1040
	ds_write_b32 v0, v16 offset:2080
	ds_write_b32 v0, v17 offset:3120
	ds_write_b32 v0, v2 offset:64
	ds_write_b32 v0, v3 offset:1104
	ds_write_b32 v0, v4 offset:2144
	ds_write_b32 v0, v5 offset:3184
	v_and_b32_e32 v0, 64, v185
	v_add_u32_e32 v6, 64, v0
	v_xor_b32_e32 v0, 1, v185
	v_cmp_lt_i32_e32 vcc, v0, v6
	v_xor_b32_e32 v2, 2, v185
	v_xor_b32_e32 v3, 4, v185
	v_cndmask_b32_e32 v0, v185, v0, vcc
	v_cmp_lt_i32_e32 vcc, v2, v6
	v_xor_b32_e32 v4, 8, v185
	v_xor_b32_e32 v5, 16, v185
	v_cndmask_b32_e32 v2, v185, v2, vcc
	v_cmp_lt_i32_e32 vcc, v3, v6
	v_xor_b32_e32 v7, 32, v185
	s_waitcnt lgkmcnt(0)
	v_cndmask_b32_e32 v3, v185, v3, vcc
	v_cmp_lt_i32_e32 vcc, v4, v6
	s_barrier
; #define LAS __attribute__((address_space(3)))
; __device__ __forceinline__ void sample_attn(Frame& F, int l, int item) {
;     ...
; #pragma unroll
;     for (int rr = 0; rr < 2; ++rr) { const int r = 2 * w + rr; f32x4 v = *(LAS f32x4*)(Ssm + r * SP + 4 * lane);
;         const float mx = wave_max(fmaxf(fmaxf(v.x, v.y), fmaxf(v.z, v.w)));
;         v.x = __builtin_amdgcn_exp2f(v.x - mx); v.y = __builtin_amdgcn_exp2f(v.y - mx); v.z = __builtin_amdgcn_exp2f(v.z - mx); v.w = __builtin_amdgcn_exp2f(v.w - mx);
;         const float inv = 1.0f / wave_sum((v.x + v.y) + (v.z + v.w));
;         *(LAS f32x4*)(Ssm + r * SP + 4 * lane) = v * inv; }
;     __syncthreads();
;     const int d = dq * 64 + (tid & 63), r0 = 2 * (tid >> 6);
;     float o0 = 0.f, o1 = 0.f;
;     const float* vp = CV + d;
	s_nop 0
	v_cndmask_b32_e32 v4, v185, v4, vcc
	v_cmp_lt_i32_e32 vcc, v5, v6
	v_lshlrev_b32_e32 v0, 2, v0
	v_lshlrev_b32_e32 v2, 2, v2
	v_cndmask_b32_e32 v5, v185, v5, vcc
	v_cmp_lt_i32_e32 vcc, v7, v6
	v_lshlrev_b32_e32 v3, 2, v3
	v_lshlrev_b32_e32 v4, 2, v4
	v_cndmask_b32_e32 v6, v185, v7, vcc
	v_lshl_add_u32 v7, v11, 4, s2
	ds_read_b128 v[14:17], v7
	v_lshlrev_b32_e32 v5, 2, v5
	v_lshlrev_b32_e32 v6, 2, v6
	s_waitcnt lgkmcnt(0)
	v_max_f32_e32 v8, v17, v17
	v_max_f32_e32 v9, v16, v16
	v_max_f32_e32 v8, v9, v8
	v_max3_f32 v8, v14, v15, v8
	ds_bpermute_b32 v9, v0, v8
	s_waitcnt lgkmcnt(0)
	v_max_f32_e32 v9, v9, v9
	v_max_f32_e32 v8, v8, v9
	ds_bpermute_b32 v9, v2, v8
	s_waitcnt lgkmcnt(0)
	v_max_f32_e32 v9, v9, v9
	v_max_f32_e32 v8, v8, v9
	ds_bpermute_b32 v9, v3, v8
	s_waitcnt lgkmcnt(0)
	v_max_f32_e32 v9, v9, v9
	v_max_f32_e32 v8, v8, v9
	ds_bpermute_b32 v9, v4, v8
	s_waitcnt lgkmcnt(0)
	v_max_f32_e32 v9, v9, v9
	v_max_f32_e32 v8, v8, v9
	ds_bpermute_b32 v9, v5, v8
	s_waitcnt lgkmcnt(0)
	v_max_f32_e32 v9, v9, v9
	v_max_f32_e32 v8, v8, v9
	ds_bpermute_b32 v9, v6, v8
	s_waitcnt lgkmcnt(0)
	v_max_f32_e32 v9, v9, v9
	v_max_f32_e32 v10, v8, v9
	v_sub_f32_e32 v9, v15, v10
	v_sub_f32_e32 v8, v14, v10
	v_exp_f32_e32 v14, v9
	v_sub_f32_e32 v9, v16, v10
	v_sub_f32_e32 v10, v17, v10
	v_exp_f32_e32 v8, v8
	v_exp_f32_e32 v9, v9
	v_exp_f32_e32 v15, v10
	s_nop 0
	v_pk_add_f32 v[16:17], v[8:9], v[14:15]
	s_nop 0
	v_add_f32_e32 v10, v16, v17
	ds_bpermute_b32 v12, v0, v10
	s_waitcnt lgkmcnt(0)
	v_add_f32_e32 v10, v10, v12
	ds_bpermute_b32 v12, v2, v10
	s_waitcnt lgkmcnt(0)
	v_add_f32_e32 v10, v10, v12
	ds_bpermute_b32 v12, v3, v10
	s_waitcnt lgkmcnt(0)
	v_add_f32_e32 v10, v10, v12
	ds_bpermute_b32 v12, v4, v10
	s_waitcnt lgkmcnt(0)
	v_add_f32_e32 v10, v10, v12
	ds_bpermute_b32 v12, v5, v10
	s_waitcnt lgkmcnt(0)
	v_add_f32_e32 v10, v10, v12
	ds_bpermute_b32 v12, v6, v10
	s_waitcnt lgkmcnt(0)
	v_add_f32_e32 v10, v10, v12
	v_div_scale_f32 v12, s[2:3], v10, v10, 1.0
	v_rcp_f32_e32 v16, v12
	s_nop 0
	v_fma_f32 v17, -v12, v16, 1.0
	v_fmac_f32_e32 v16, v17, v16
	v_div_scale_f32 v17, vcc, 1.0, v10, 1.0
	v_mul_f32_e32 v18, v17, v16
	v_fma_f32 v19, -v12, v18, v17
	v_fmac_f32_e32 v18, v19, v16
	v_fma_f32 v12, -v12, v18, v17
	v_div_fmas_f32 v12, v12, v16, v18
	v_div_fixup_f32 v10, v12, v10, 1.0
	v_mov_b32_e32 v16, v9
	v_mov_b32_e32 v17, v15
	v_mov_b32_e32 v9, v14
	v_pk_mul_f32 v[16:17], v[16:17], v[10:11] op_sel_hi:[1,0]
	v_pk_mul_f32 v[14:15], v[8:9], v[10:11] op_sel_hi:[1,0]
	ds_write_b128 v7, v[14:17]
	ds_read_b128 v[14:17], v7 offset:1040
	s_waitcnt lgkmcnt(0)
	v_max_f32_e32 v8, v17, v17
	v_max_f32_e32 v9, v16, v16
	v_max_f32_e32 v8, v9, v8
	v_max3_f32 v8, v14, v15, v8
	ds_bpermute_b32 v9, v0, v8
	s_waitcnt lgkmcnt(0)
	v_max_f32_e32 v9, v9, v9
	v_max_f32_e32 v8, v8, v9
	ds_bpermute_b32 v9, v2, v8
	s_waitcnt lgkmcnt(0)
	v_max_f32_e32 v9, v9, v9
	v_max_f32_e32 v8, v8, v9
	ds_bpermute_b32 v9, v3, v8
	s_waitcnt lgkmcnt(0)
	v_max_f32_e32 v9, v9, v9
	v_max_f32_e32 v8, v8, v9
	ds_bpermute_b32 v9, v4, v8
	s_waitcnt lgkmcnt(0)
	v_max_f32_e32 v9, v9, v9
	v_max_f32_e32 v8, v8, v9
	ds_bpermute_b32 v9, v5, v8
	s_waitcnt lgkmcnt(0)
	v_max_f32_e32 v9, v9, v9
	v_max_f32_e32 v8, v8, v9
	ds_bpermute_b32 v9, v6, v8
	s_waitcnt lgkmcnt(0)
	v_max_f32_e32 v9, v9, v9
	v_max_f32_e32 v10, v8, v9
	v_sub_f32_e32 v9, v15, v10
	v_sub_f32_e32 v8, v14, v10
	v_exp_f32_e32 v14, v9
	v_sub_f32_e32 v9, v16, v10
	v_sub_f32_e32 v10, v17, v10
	v_exp_f32_e32 v8, v8
	v_exp_f32_e32 v9, v9
	v_exp_f32_e32 v15, v10
	s_nop 0
	v_pk_add_f32 v[16:17], v[8:9], v[14:15]
	s_nop 0
	v_add_f32_e32 v10, v16, v17
	ds_bpermute_b32 v0, v0, v10
	s_waitcnt lgkmcnt(0)
	v_add_f32_e32 v0, v10, v0
	ds_bpermute_b32 v2, v2, v0
	s_waitcnt lgkmcnt(0)
	v_add_f32_e32 v0, v0, v2
	ds_bpermute_b32 v2, v3, v0
	s_waitcnt lgkmcnt(0)
	v_add_f32_e32 v0, v0, v2
	ds_bpermute_b32 v2, v4, v0
	s_waitcnt lgkmcnt(0)
	v_add_f32_e32 v0, v0, v2
	ds_bpermute_b32 v2, v5, v0
	s_waitcnt lgkmcnt(0)
	v_add_f32_e32 v0, v0, v2
	ds_bpermute_b32 v2, v6, v0
	s_waitcnt lgkmcnt(0)
	v_add_f32_e32 v0, v0, v2
	v_div_scale_f32 v2, s[2:3], v0, v0, 1.0
	v_rcp_f32_e32 v3, v2
	s_movk_i32 s2, 0x820
	s_and_b32 s3, s18, 0x300
	v_fma_f32 v4, -v2, v3, 1.0
	v_fmac_f32_e32 v3, v4, v3
	v_div_scale_f32 v4, vcc, 1.0, v0, 1.0
	v_mul_f32_e32 v5, v4, v3
	v_fma_f32 v6, -v2, v5, v4
	v_fmac_f32_e32 v5, v6, v3
	v_fma_f32 v2, -v2, v5, v4
	v_div_fmas_f32 v2, v2, v3, v5
	v_div_fixup_f32 v0, v2, v0, 1.0
	v_mov_b32_e32 v2, v9
	v_mov_b32_e32 v3, v15
	v_mov_b32_e32 v9, v14
	v_pk_mul_f32 v[4:5], v[2:3], v[0:1] op_sel_hi:[1,0]
	v_pk_mul_f32 v[2:3], v[8:9], v[0:1] op_sel_hi:[1,0]
	v_mul_lo_u32 v0, v13, s2
	s_or_b32 s2, s4, s19
	s_add_u32 s2, s60, s2
	ds_write_b128 v7, v[2:5] offset:1040
	v_add_u32_e32 v7, 0, v0
	v_lshl_or_b32 v0, v11, 2, s3
	s_addc_u32 s3, s61, s5
	v_mov_b32_e32 v4, 0
	v_lshl_add_u64 v[2:3], s[2:3], 0, v[0:1]
	s_movk_i32 s4, 0xffe0
	v_mov_b32_e32 v5, v4
	s_waitcnt lgkmcnt(0)
	s_barrier

; #define LAS __attribute__((address_space(3)))
; template <int MODE>
; __device__ __forceinline__ void sgemm_phase(LAS unsigned char* lds, const SgArgs g, int ntiles, int bid, int G) {
;     ...
;     for (int t = bid; t < ntiles; t += G) {
;         const int ct = t >> 3, rt = t & 7;
;         const int brow0 = MODE == 0 ? 256 * (ct >> 2) + 32 * (ct & 3) : 64 * ct, brow1 = MODE == 0 ? brow0 + 128 : brow0 + 32;
;         const bf16_t* ap = g.A + (size_t)(MP + rt * 32 + r32) * g.lda + wave * kw + hi * 8;
;         const bf16_t* bp0 = g.Bt + (size_t)(brow0 + r32) * g.ldb + wave * kw + hi * 8;
;         const bf16_t* bp1 = g.Bt + (size_t)(brow1 + r32) * g.ldb + wave * kw + hi * 8;
;         f32x16 c0 = {}, c1 = {};
;         for (int k0 = 0; k0 < kw; k0 += 128) {
;             bf16x8 a[8], b0[8], b1[8];
; #pragma unroll
;             for (int i = 0; i < 8; ++i) if (k0 + 16 * i < kw) { a[i] = *(const bf16x8*)(ap + k0 + 16 * i); b0[i] = *(const bf16x8*)(bp0 + k0 + 16 * i); b1[i] = *(const bf16x8*)(bp1 + k0 + 16 * i); }
;             asm volatile("" ::: "memory");
; #pragma unroll
;             for (int i = 0; i < 8; ++i) if (k0 + 16 * i < kw) { c0 = __builtin_amdgcn_mfma_f32_32x32x16_bf16(a[i], b0[i], c0, 0, 0, 0); c1 = __builtin_amdgcn_mfma_f32_32x32x16_bf16(a[i], b1[i], c1, 0, 0, 0); }
;         }
;         LAS float* red = (LAS float*)lds + wave * 2048;
; #pragma unroll
;         for (int r = 0; r < 16; ++r) { const int row = (r & 3) + 8 * (r >> 2) + 4 * hi; red[row * 64 + r32] = c0[r]; red[row * 64 + 32 + r32] = c1[r]; }
;         __syncthreads();
.LBB0_760:
	s_ashr_i32 s11, s10, 5
	s_and_b32 s28, s7, 0x60
	s_lshl_b32 s3, s11, 8
	s_and_b32 s29, s9, 0xe0
	s_or_b32 s3, s3, s28
	s_bitset1_b32 s29, 15
	v_or_b32_e32 v2, s3, v44
	v_or_b32_e32 v0, s29, v44
	v_ashrrev_i32_e32 v3, 31, v2
	v_lshlrev_b32_e32 v0, 11, v0
	v_or_b32_e32 v4, 0x80, v2
	v_lshlrev_b64 v[2:3], 11, v[2:3]
	v_lshl_add_u64 v[72:73], v[38:39], 0, v[0:1]
	v_ashrrev_i32_e32 v5, 31, v4
	v_lshl_add_u64 v[76:77], v[40:41], 0, v[2:3]
	v_lshlrev_b64 v[6:7], 11, v[4:5]
	v_lshl_add_u64 v[78:79], v[40:41], 0, v[6:7]
	global_load_dwordx4 v[190:193], v[72:73], off
	global_load_dwordx4 v[222:225], v[76:77], off
	global_load_dwordx4 v[132:135], v[78:79], off
	global_load_dwordx4 v[194:197], v[72:73], off offset:32
	global_load_dwordx4 v[226:229], v[76:77], off offset:32
	global_load_dwordx4 v[136:139], v[78:79], off offset:32
	global_load_dwordx4 v[198:201], v[72:73], off offset:64
	global_load_dwordx4 v[230:233], v[76:77], off offset:64
	global_load_dwordx4 v[140:143], v[78:79], off offset:64
	global_load_dwordx4 v[202:205], v[72:73], off offset:96
	global_load_dwordx4 v[234:237], v[76:77], off offset:96
	global_load_dwordx4 v[144:147], v[78:79], off offset:96
	global_load_dwordx4 v[206:209], v[72:73], off offset:128
	global_load_dwordx4 v[238:241], v[76:77], off offset:128
	global_load_dwordx4 v[148:151], v[78:79], off offset:128
	global_load_dwordx4 v[210:213], v[72:73], off offset:160
	global_load_dwordx4 v[242:245], v[76:77], off offset:160
	global_load_dwordx4 v[152:155], v[78:79], off offset:160
	global_load_dwordx4 v[214:217], v[72:73], off offset:192
	global_load_dwordx4 v[246:249], v[76:77], off offset:192
	global_load_dwordx4 v[156:159], v[78:79], off offset:192
	global_load_dwordx4 v[218:221], v[72:73], off offset:224
	global_load_dwordx4 v[250:253], v[76:77], off offset:224
	global_load_dwordx4 v[164:167], v[78:79], off offset:224
	v_add_u32_e32 v0, 0x800, v45
	s_lshl_b32 s30, s11, 7
	s_lshl_b32 s46, s28, 1
	s_ashr_i32 s31, s30, 31
	v_mov_b32_e32 v43, v1
	s_add_i32 s10, s10, s86
	s_add_i32 s9, s9, s87
	s_add_i32 s7, s7, s37
	s_cmpk_lt_i32 s10, 0x2c0
	v_add_u32_e32 v72, 0x6000, v47
	v_add_u32_e32 v73, 0x8000, v47
	v_add_u32_e32 v74, 0xa000, v47
	v_add_u32_e32 v60, 0x1000, v45
	v_add_u32_e32 v61, 0x1800, v45
	v_add_u32_e32 v62, 0x2000, v47
	v_add_u32_e32 v63, 0x4000, v47
	v_add_u32_e32 v50, s29, v46
	v_ashrrev_i32_e32 v51, 31, v50
	v_mov_b64_e32 v[48:49], s[16:17]
	v_add_u32_e32 v64, 0xc000, v47
	v_add_u32_e32 v65, 0xe000, v47
	v_lshlrev_b64 v[52:53], 6, v[50:51]
	v_lshl_add_u64 v[52:53], s[12:13], 0, v[52:53]
	s_waitcnt vmcnt(21)
	v_mfma_f32_32x32x16_bf16 v[2:17], v[190:193], v[222:225], 0
	v_mfma_f32_32x32x16_bf16 v[18:33], v[190:193], v[132:135], 0
	s_waitcnt vmcnt(18)
	v_mfma_f32_32x32x16_bf16 v[2:17], v[194:197], v[226:229], v[2:17]
	v_mfma_f32_32x32x16_bf16 v[18:33], v[194:197], v[136:139], v[18:33]
	s_waitcnt vmcnt(15)
	v_mfma_f32_32x32x16_bf16 v[2:17], v[198:201], v[230:233], v[2:17]
	v_mfma_f32_32x32x16_bf16 v[18:33], v[198:201], v[140:143], v[18:33]
	s_waitcnt vmcnt(12)
	v_mfma_f32_32x32x16_bf16 v[2:17], v[202:205], v[234:237], v[2:17]
	v_mfma_f32_32x32x16_bf16 v[18:33], v[202:205], v[144:147], v[18:33]
	s_waitcnt vmcnt(9)
	v_mfma_f32_32x32x16_bf16 v[2:17], v[206:209], v[238:241], v[2:17]
	v_mfma_f32_32x32x16_bf16 v[18:33], v[206:209], v[148:151], v[18:33]
	s_waitcnt vmcnt(6)
	v_mfma_f32_32x32x16_bf16 v[2:17], v[210:213], v[242:245], v[2:17]
	v_mfma_f32_32x32x16_bf16 v[18:33], v[210:213], v[152:155], v[18:33]
	s_waitcnt vmcnt(3)
	v_mfma_f32_32x32x16_bf16 v[2:17], v[214:217], v[246:249], v[2:17]
	v_mfma_f32_32x32x16_bf16 v[18:33], v[214:217], v[156:159], v[18:33]
	s_waitcnt vmcnt(0)
	v_mfma_f32_32x32x16_bf16 v[2:17], v[218:221], v[250:253], v[2:17]
	v_mfma_f32_32x32x16_bf16 v[18:33], v[218:221], v[164:167], v[18:33]
	s_nop 11
	ds_write2_b32 v45, v2, v18 offset1:32
	ds_write2_b32 v45, v3, v19 offset0:64 offset1:96
	ds_write2_b32 v45, v4, v20 offset0:128 offset1:160
	ds_write2_b32 v45, v5, v21 offset0:192 offset1:224
	ds_write2_b32 v0, v6, v22 offset1:32
	ds_write2_b32 v0, v7, v23 offset0:64 offset1:96
	ds_write2_b32 v0, v8, v24 offset0:128 offset1:160
	ds_write2_b32 v0, v9, v25 offset0:192 offset1:224
	ds_write2_b32 v60, v10, v26 offset1:32
	ds_write2_b32 v60, v11, v27 offset0:64 offset1:96
	ds_write2_b32 v60, v12, v28 offset0:128 offset1:160
	ds_write2_b32 v60, v13, v29 offset0:192 offset1:224
	ds_write2_b32 v61, v14, v30 offset1:32
	ds_write2_b32 v61, v15, v31 offset0:64 offset1:96
	ds_write2_b32 v61, v16, v32 offset0:128 offset1:160
	ds_write2_b32 v61, v17, v33 offset0:192 offset1:224
	s_waitcnt lgkmcnt(0)
	s_barrier
; #define LAS __attribute__((address_space(3)))
; __device__ __forceinline__ unsigned cvt_pk_bf16(float lo, float hi) { unsigned r; asm volatile("v_cvt_pk_bf16_f32 %0, %1, %2" : "=v"(r) : "v"(lo), "v"(hi)); return r; }
; __device__ __forceinline__ float row_rstd(const float* ssq, int row) {
;     const f32x4* p = (const f32x4*)(ssq + (size_t)row * 16);
;     const f32x4 a = p[0], b = p[1], c = p[2], d = p[3];
;     const float s = (((a.x + a.y) + (a.z + a.w)) + ((b.x + b.y) + (b.z + b.w))) + (((c.x + c.y) + (c.z + c.w)) + ((d.x + d.y) + (d.z + d.w)));
;     return rsqrtf(s * (1.0f / 1024.0f) + EPS);
; template <int MODE>
; __device__ __forceinline__ void sgemm_phase(LAS unsigned char* lds, const SgArgs g, int ntiles, int bid, int G) {
;     ...
;         const int row = tid >> 4, q = tid & 15; float v0 = 0.f, v1 = 0.f, v2 = 0.f, v3 = 0.f;
; #pragma unroll
;         for (int w = 0; w < 8; ++w) { const LAS float* p = (const LAS float*)lds + w * 2048 + row * 64 + 2 * q; const f32x2 lo = *(const LAS f32x2*)p, hi2 = *(const LAS f32x2*)(p + 32); v0 += lo.x; v1 += lo.y; v2 += hi2.x; v3 += hi2.y; }
;         const int grow = MP + rt * 32 + row;
;         if (MODE == 0) {
;             const float rs = row_rstd(g.ssq_in, grow); const float g0 = v0 * rs, g1 = v1 * rs, u0 = v2 * rs, u1 = v3 * rs;
;             const float a0 = g0 * __builtin_amdgcn_rcpf(1.0f + __builtin_amdgcn_exp2f(-1.4426950408889634f * g0)) * u0, a1 = g1 * __builtin_amdgcn_rcpf(1.0f + __builtin_amdgcn_exp2f(-1.4426950408889634f * g1)) * u1;
;             *(unsigned*)(g.O + (size_t)grow * g.ldc + 128 * (ct >> 2) + 32 * (ct & 3) + 2 * q) = cvt_pk_bf16(a0, a1);
	flat_load_dwordx4 v[2:5], v[52:53]
	flat_load_dwordx4 v[6:9], v[52:53] offset:32
	flat_load_dwordx4 v[10:13], v[52:53] offset:16
	flat_load_dwordx4 v[14:17], v[52:53] offset:48
	v_mad_i64_i32 v[18:19], s[28:29], v50, s80, v[48:49]
	v_lshl_add_u64 v[18:19], s[30:31], 1, v[18:19]
	v_lshl_add_u64 v[18:19], v[18:19], 0, s[46:47]
	v_lshl_add_u64 v[60:61], v[18:19], 0, v[42:43]
	ds_read2_b64 v[18:21], v47 offset1:16
	ds_read2_b64 v[22:25], v62 offset1:16
	ds_read2_b64 v[26:29], v63 offset1:16
	ds_read2_b64 v[30:33], v72 offset1:16
	ds_read2_b64 v[34:37], v73 offset1:16
	ds_read2_b64 v[48:51], v74 offset1:16
	ds_read2_b64 v[52:55], v64 offset1:16
	ds_read2_b64 v[56:59], v65 offset1:16
	s_waitcnt lgkmcnt(0)
	v_mov_b32_e32 v63, v18
	v_mov_b32_e32 v18, v21
	v_mov_b32_e32 v65, v22
	v_mov_b32_e32 v22, v25
	v_pk_add_f32 v[18:19], v[18:19], 0 op_sel_hi:[1,0]
	v_mov_b32_e32 v62, v20
	v_pk_add_f32 v[18:19], v[18:19], v[22:23]
	v_mov_b32_e32 v64, v24
	v_pk_add_f32 v[20:21], v[62:63], 0 op_sel_hi:[1,0]
	v_mov_b32_e32 v66, v28
	v_mov_b32_e32 v67, v26
	v_pk_add_f32 v[20:21], v[20:21], v[64:65]
	v_mov_b32_e32 v68, v32
	v_mov_b32_e32 v69, v30
	v_mov_b32_e32 v26, v29
	v_pk_add_f32 v[20:21], v[20:21], v[66:67]
	v_mov_b32_e32 v70, v36
	v_mov_b32_e32 v71, v34
	v_mov_b32_e32 v30, v33
	v_pk_add_f32 v[18:19], v[18:19], v[26:27]
	v_pk_add_f32 v[20:21], v[20:21], v[68:69]
	v_mov_b32_e32 v72, v50
	v_mov_b32_e32 v73, v48
	v_mov_b32_e32 v34, v37
	v_pk_add_f32 v[18:19], v[18:19], v[30:31]
	v_pk_add_f32 v[20:21], v[20:21], v[70:71]
	v_mov_b32_e32 v74, v54
	v_mov_b32_e32 v75, v52
	v_mov_b32_e32 v48, v51
	v_pk_add_f32 v[18:19], v[18:19], v[34:35]
	v_pk_add_f32 v[20:21], v[20:21], v[72:73]
	v_mov_b32_e32 v76, v58
	v_mov_b32_e32 v77, v56
	v_mov_b32_e32 v52, v55
	v_pk_add_f32 v[18:19], v[18:19], v[48:49]
	v_pk_add_f32 v[20:21], v[20:21], v[74:75]
	v_mov_b32_e32 v56, v59
	v_pk_add_f32 v[18:19], v[18:19], v[52:53]
	v_pk_add_f32 v[20:21], v[20:21], v[76:77]
	v_pk_add_f32 v[18:19], v[18:19], v[56:57]
	s_waitcnt vmcnt(0)
	v_mov_b32_e32 v22, v2
	v_mov_b32_e32 v23, v6
	v_mov_b32_e32 v6, v3
	v_mov_b32_e32 v2, v4
	v_mov_b32_e32 v3, v8
	v_mov_b32_e32 v8, v5
	v_mov_b32_e32 v4, v10
	v_mov_b32_e32 v5, v14
	v_mov_b32_e32 v14, v11
	v_mov_b32_e32 v10, v12
	v_mov_b32_e32 v11, v16
	v_mov_b32_e32 v16, v13
	v_pk_add_f32 v[6:7], v[22:23], v[6:7]
	v_pk_add_f32 v[2:3], v[2:3], v[8:9]
	v_pk_add_f32 v[4:5], v[4:5], v[14:15]
	v_pk_add_f32 v[8:9], v[10:11], v[16:17]
	v_pk_add_f32 v[2:3], v[6:7], v[2:3]
	v_pk_add_f32 v[4:5], v[4:5], v[8:9]
	s_nop 0
	v_pk_add_f32 v[2:3], v[2:3], v[4:5]
	s_nop 0
	v_add_f32_e32 v0, v2, v3
	v_fmamk_f32 v0, v0, 0x3a800000, v162
	v_mul_f32_e32 v2, 0x4b800000, v0
	v_cmp_gt_f32_e32 vcc, s69, v0
	s_nop 1
	v_cndmask_b32_e32 v0, v0, v2, vcc
	v_rsq_f32_e32 v0, v0
	s_nop 0
	v_mul_f32_e32 v2, 0x45800000, v0
	v_cndmask_b32_e32 v0, v0, v2, vcc
	v_pk_mul_f32 v[2:3], v[20:21], v[0:1] op_sel_hi:[1,0]
	v_pk_mul_f32 v[4:5], v[18:19], v[0:1] op_sel_hi:[1,0]
	v_mul_f32_e32 v0, 0xbfb8aa3b, v3
	v_mul_f32_e32 v6, 0xbfb8aa3b, v5
	v_exp_f32_e32 v0, v0
	v_exp_f32_e32 v6, v6
	v_add_f32_e32 v0, 1.0, v0
	v_add_f32_e32 v6, 1.0, v6
	v_rcp_f32_e32 v0, v0
	v_rcp_f32_e32 v6, v6
	v_mul_f32_e32 v0, v3, v0
	v_mul_f32_e32 v3, v5, v6
	v_mul_f32_e32 v0, v2, v0
	v_mul_f32_e32 v2, v4, v3
	v_cvt_pk_bf16_f32 v0, v0, v2
	flat_store_dword v[60:61], v0
	s_waitcnt lgkmcnt(0)
	s_barrier
	s_cbranch_scc1 .LBB0_760
	s_branch .LBB0_755
